# v45 plus rebalanced MFMA-gap fill: p1 packing moved into the PV gaps, exps 3 per PV gap, chain adds 5-6 per QK gap
# speedup vs baseline: 1.0126x; 1.0047x over previous
; __device__ __forceinline__ void finishSM2(f32x16& p0, f32x16& p1, float alpha, float& l_reg, bf16x8& pa0, bf16x8& pa1, bf16x8& pa2, bf16x8& pa3) {
; #pragma unroll
;   for (int r = 0; r < 16; ++r) p1[r] = __builtin_amdgcn_exp2f(p1[r]);
;   float ps = 0;
; #pragma unroll
;   for (int r = 0; r < 16; ++r) ps += p0[r];
; #pragma unroll
;   for (int r = 0; r < 16; ++r) ps += p1[r];
;   { auto rr = __builtin_amdgcn_permlane32_swap(__float_as_uint(ps), __float_as_uint(ps), false, false);
;     ps = __uint_as_float(rr[0]) + __uint_as_float(rr[1]); }
;   l_reg = l_reg * alpha + ps;
;     ...
;   PK8(p0, 0, pa0); PK8(p0, 8, pa1); PK8(p1, 0, pa2); PK8(p1, 8, pa3);
;     ...
; }
; __device__ __forceinline__ void kload12(bf16x8* kf, const LAS char* Ks, int r32, int hi) {
;   const LAS char* kb = Ks + hi * 1024 + r32 * 16;
; #pragma unroll
;   for (int d0 = 0; d0 < 6; ++d0) { kf[2 * d0] = *(const LAS bf16x8*)(kb + d0 * 2048); kf[2 * d0 + 1] = *(const LAS bf16x8*)(kb + d0 * 2048 + 512); }
; }
; __device__ __forceinline__ void qkt3(f32x16& p0, f32x16& p1, const bf16x8* kf, const bf16x8* qr) {
;   p0 = f32x16{}; p1 = f32x16{};
; #pragma unroll
;   for (int d0 = 0; d0 < 6; ++d0) {
;     p0 = __builtin_amdgcn_mfma_f32_32x32x16_bf16(kf[2 * d0], qr[d0], p0, 0, 0, 0);
;     p1 = __builtin_amdgcn_mfma_f32_32x32x16_bf16(kf[2 * d0 + 1], qr[d0], p1, 0, 0, 0); }
; }
; __device__ __forceinline__ void vload16(s16x4* vf, int vb) {
;   vf[0] = tr_read<0>(vb); vf[1] = tr_read<512>(vb); vf[2] = tr_read<1024>(vb); vf[3] = tr_read<1536>(vb);
;   vf[4] = tr_read<2048>(vb); vf[5] = tr_read<2560>(vb); vf[6] = tr_read<3072>(vb); vf[7] = tr_read<3584>(vb);
;   vf[8] = tr_read<4096>(vb); vf[9] = tr_read<4608>(vb); vf[10] = tr_read<5120>(vb); vf[11] = tr_read<5632>(vb);
;   vf[12] = tr_read<6144>(vb); vf[13] = tr_read<6656>(vb); vf[14] = tr_read<7168>(vb); vf[15] = tr_read<7680>(vb);
; }
; __device__ __forceinline__ void pv3(f32x16* o, const s16x4* vf, bf16x8 pa0, bf16x8 pa1, bf16x8 pa2, bf16x8 pa3) {
;     ...
;   o[0] = __builtin_amdgcn_mfma_f32_32x32x16_bf16(pa0, PKV(0), o[0], 0, 0, 0);
;   o[1] = __builtin_amdgcn_mfma_f32_32x32x16_bf16(pa0, PKV(8), o[1], 0, 0, 0);
;   o[0] = __builtin_amdgcn_mfma_f32_32x32x16_bf16(pa1, PKV(2), o[0], 0, 0, 0);
;   o[1] = __builtin_amdgcn_mfma_f32_32x32x16_bf16(pa1, PKV(10), o[1], 0, 0, 0);
;   o[0] = __builtin_amdgcn_mfma_f32_32x32x16_bf16(pa2, PKV(4), o[0], 0, 0, 0);
.Lwd_a:
	s_barrier
	s_waitcnt lgkmcnt(0)
	s_setprio 1
	v_mfma_f32_32x32x16_bf16 v[80:95], v[48:51], v[116:119], v[238:253]
	v_exp_f32_e32 v64, v64
	v_add_f32_e32 v213, v32, v213
	ds_read_b64_tr_b16 v[148:149], v217 offset:0
	v_exp_f32_e32 v65, v65
	v_add_f32_e32 v213, v33, v213
	ds_read_b64_tr_b16 v[150:151], v217 offset:512
	v_mfma_f32_32x32x16_bf16 v[48:63], v[52:55], v[116:119], v[238:253]
	v_exp_f32_e32 v66, v66
	v_add_f32_e32 v213, v34, v213
	ds_read_b64_tr_b16 v[140:141], v217 offset:1024
	v_exp_f32_e32 v67, v67
	v_add_f32_e32 v213, v35, v213
	ds_read_b64_tr_b16 v[142:143], v217 offset:1536
	v_mfma_f32_32x32x16_bf16 v[80:95], v[188:191], v[112:115], v[80:95]
	v_exp_f32_e32 v68, v68
	v_add_f32_e32 v213, v36, v213
	ds_read_b64_tr_b16 v[132:133], v217 offset:2048
	v_exp_f32_e32 v69, v69
	v_add_f32_e32 v213, v37, v213
	ds_read_b64_tr_b16 v[134:135], v217 offset:2560
	v_mfma_f32_32x32x16_bf16 v[48:63], v[184:187], v[112:115], v[48:63]
	v_exp_f32_e32 v70, v70
	v_add_f32_e32 v213, v38, v213
	ds_read_b64_tr_b16 v[124:125], v217 offset:3072
	v_exp_f32_e32 v71, v71
	v_add_f32_e32 v213, v39, v213
	ds_read_b64_tr_b16 v[126:127], v217 offset:3584
	v_mfma_f32_32x32x16_bf16 v[80:95], v[180:183], v[108:111], v[80:95]
	v_exp_f32_e32 v72, v72
	v_add_f32_e32 v213, v40, v213
	ds_read_b64_tr_b16 v[144:145], v217 offset:4096
	v_exp_f32_e32 v73, v73
	v_add_f32_e32 v213, v41, v213
	ds_read_b64_tr_b16 v[146:147], v217 offset:4608
	v_mfma_f32_32x32x16_bf16 v[48:63], v[176:179], v[108:111], v[48:63]
	v_exp_f32_e32 v74, v74
	v_add_f32_e32 v213, v42, v213
	ds_read_b64_tr_b16 v[136:137], v217 offset:5120
	v_exp_f32_e32 v75, v75
	v_add_f32_e32 v213, v43, v213
	ds_read_b64_tr_b16 v[138:139], v217 offset:5632
	v_mfma_f32_32x32x16_bf16 v[80:95], v[172:175], v[104:107], v[80:95]
	v_exp_f32_e32 v76, v76
	v_add_f32_e32 v213, v44, v213
	ds_read_b64_tr_b16 v[128:129], v217 offset:6144
	v_exp_f32_e32 v77, v77
	v_add_f32_e32 v213, v45, v213
	ds_read_b64_tr_b16 v[130:131], v217 offset:6656
	v_mfma_f32_32x32x16_bf16 v[48:63], v[168:171], v[104:107], v[48:63]
	v_exp_f32_e32 v78, v78
	v_add_f32_e32 v213, v46, v213
	ds_read_b64_tr_b16 v[120:121], v217 offset:7168
	v_exp_f32_e32 v79, v79
	v_add_f32_e32 v213, v47, v213
	ds_read_b64_tr_b16 v[122:123], v217 offset:7680
	v_mfma_f32_32x32x16_bf16 v[80:95], v[164:167], v[100:103], v[80:95]
	v_add_f32_e32 v237, v64, v65
	v_add_f32_e32 v237, v66, v237
	v_add_f32_e32 v237, v67, v237
	v_add_f32_e32 v237, v68, v237
	v_add_f32_e32 v237, v69, v237
	v_add_f32_e32 v237, v70, v237
	v_mfma_f32_32x32x16_bf16 v[48:63], v[160:163], v[100:103], v[48:63]
	v_add_f32_e32 v237, v71, v237
	v_add_f32_e32 v237, v72, v237
	v_add_f32_e32 v237, v73, v237
	v_add_f32_e32 v237, v74, v237
	v_add_f32_e32 v237, v75, v237
	v_mfma_f32_32x32x16_bf16 v[80:95], v[156:159], v[96:99], v[80:95]
	v_add_f32_e32 v237, v76, v237
	v_add_f32_e32 v237, v77, v237
	v_add_f32_e32 v237, v78, v237
	v_add_f32_e32 v237, v79, v237
	v_add_f32_e32 v213, v237, v213
	v_cvt_pk_bf16_f32 v32, v32, v33
	v_mfma_f32_32x32x16_bf16 v[48:63], v[152:155], v[96:99], v[48:63]
	v_cvt_pk_bf16_f32 v33, v34, v35
	v_cvt_pk_bf16_f32 v34, v36, v37
	v_cvt_pk_bf16_f32 v35, v38, v39
	v_cvt_pk_bf16_f32 v36, v40, v41
	v_cvt_pk_bf16_f32 v37, v42, v43
	v_cvt_pk_bf16_f32 v38, v44, v45
	s_waitcnt lgkmcnt(0)
	v_mfma_f32_32x32x16_bf16 v[0:15], v[32:35], v[148:151], v[0:15]
	v_cvt_pk_bf16_f32 v39, v46, v47
	v_cvt_pk_bf16_f32 v64, v64, v65
	v_cvt_pk_bf16_f32 v65, v66, v67
	v_cvt_pk_bf16_f32 v66, v68, v69
	v_mfma_f32_32x32x16_bf16 v[16:31], v[32:35], v[144:147], v[16:31]
	v_cvt_pk_bf16_f32 v67, v70, v71
	v_cvt_pk_bf16_f32 v68, v72, v73
	v_cvt_pk_bf16_f32 v69, v74, v75
	v_cvt_pk_bf16_f32 v70, v76, v77
	v_cvt_pk_bf16_f32 v71, v78, v79
	v_mfma_f32_32x32x16_bf16 v[0:15], v[36:39], v[140:143], v[0:15]
	v_exp_f32_e32 v40, v88
	v_exp_f32_e32 v41, v89
	v_exp_f32_e32 v42, v90
	v_mfma_f32_32x32x16_bf16 v[16:31], v[36:39], v[136:139], v[16:31]
	v_exp_f32_e32 v43, v91
	v_exp_f32_e32 v44, v92
	v_exp_f32_e32 v45, v93
	v_mfma_f32_32x32x16_bf16 v[0:15], v[64:67], v[132:135], v[0:15]
	v_exp_f32_e32 v46, v94
	v_exp_f32_e32 v47, v95
	v_exp_f32_e32 v32, v80
	v_mfma_f32_32x32x16_bf16 v[16:31], v[64:67], v[128:131], v[16:31]
	v_exp_f32_e32 v33, v81
	v_exp_f32_e32 v34, v82
	v_exp_f32_e32 v35, v83
	v_mfma_f32_32x32x16_bf16 v[0:15], v[68:71], v[124:127], v[0:15]
	v_exp_f32_e32 v36, v84
	v_exp_f32_e32 v37, v85
	v_mfma_f32_32x32x16_bf16 v[16:31], v[68:71], v[120:123], v[16:31]
	v_exp_f32_e32 v38, v86
	v_exp_f32_e32 v39, v87
	s_setprio 0
	s_barrier
	v_max3_f32 v215, v80, v81, v82
	v_max3_f32 v215, v215, v83, v84
	v_max3_f32 v215, v215, v85, v86
	v_max3_f32 v215, v215, v87, v88
	v_max3_f32 v215, v215, v89, v90
	v_max3_f32 v215, v215, v91, v92
	v_max3_f32 v215, v215, v93, v94
	v_max3_f32 v215, v215, v95, v48
	v_max3_f32 v215, v215, v49, v50
	v_max3_f32 v215, v215, v51, v52
	v_max3_f32 v215, v215, v53, v54
	v_max3_f32 v215, v215, v55, v56
	v_max3_f32 v215, v215, v57, v58
	v_max3_f32 v215, v215, v59, v60
	v_max3_f32 v215, v215, v61, v62
	v_max_f32_e32 v215, v215, v63
	v_cmp_nge_f32_e32 vcc, s23, v215
	s_nop 3
	s_cmp_lg_u64 vcc, 0
	s_cbranch_scc1 .Lrare_a

; __device__ __forceinline__ void finishSM2(f32x16& p0, f32x16& p1, float alpha, float& l_reg, bf16x8& pa0, bf16x8& pa1, bf16x8& pa2, bf16x8& pa3) {
; #pragma unroll
;   for (int r = 0; r < 16; ++r) p1[r] = __builtin_amdgcn_exp2f(p1[r]);
;   float ps = 0;
; #pragma unroll
;   for (int r = 0; r < 16; ++r) ps += p0[r];
; #pragma unroll
;   for (int r = 0; r < 16; ++r) ps += p1[r];
;   { auto rr = __builtin_amdgcn_permlane32_swap(__float_as_uint(ps), __float_as_uint(ps), false, false);
;     ps = __uint_as_float(rr[0]) + __uint_as_float(rr[1]); }
;   l_reg = l_reg * alpha + ps;
;     ...
;   PK8(p0, 0, pa0); PK8(p0, 8, pa1); PK8(p1, 0, pa2); PK8(p1, 8, pa3);
;     ...
; }
; __device__ __forceinline__ void kload12(bf16x8* kf, const LAS char* Ks, int r32, int hi) {
;   const LAS char* kb = Ks + hi * 1024 + r32 * 16;
; #pragma unroll
;   for (int d0 = 0; d0 < 6; ++d0) { kf[2 * d0] = *(const LAS bf16x8*)(kb + d0 * 2048); kf[2 * d0 + 1] = *(const LAS bf16x8*)(kb + d0 * 2048 + 512); }
; }
; __device__ __forceinline__ void qkt3(f32x16& p0, f32x16& p1, const bf16x8* kf, const bf16x8* qr) {
;   p0 = f32x16{}; p1 = f32x16{};
; #pragma unroll
;   for (int d0 = 0; d0 < 6; ++d0) {
;     p0 = __builtin_amdgcn_mfma_f32_32x32x16_bf16(kf[2 * d0], qr[d0], p0, 0, 0, 0);
;     p1 = __builtin_amdgcn_mfma_f32_32x32x16_bf16(kf[2 * d0 + 1], qr[d0], p1, 0, 0, 0); }
; }
; __device__ __forceinline__ void vload16(s16x4* vf, int vb) {
;   vf[0] = tr_read<0>(vb); vf[1] = tr_read<512>(vb); vf[2] = tr_read<1024>(vb); vf[3] = tr_read<1536>(vb);
;   vf[4] = tr_read<2048>(vb); vf[5] = tr_read<2560>(vb); vf[6] = tr_read<3072>(vb); vf[7] = tr_read<3584>(vb);
;   vf[8] = tr_read<4096>(vb); vf[9] = tr_read<4608>(vb); vf[10] = tr_read<5120>(vb); vf[11] = tr_read<5632>(vb);
;   vf[12] = tr_read<6144>(vb); vf[13] = tr_read<6656>(vb); vf[14] = tr_read<7168>(vb); vf[15] = tr_read<7680>(vb);
; }
; __device__ __forceinline__ void pv3(f32x16* o, const s16x4* vf, bf16x8 pa0, bf16x8 pa1, bf16x8 pa2, bf16x8 pa3) {
;     ...
;   o[0] = __builtin_amdgcn_mfma_f32_32x32x16_bf16(pa0, PKV(0), o[0], 0, 0, 0);
;   o[1] = __builtin_amdgcn_mfma_f32_32x32x16_bf16(pa0, PKV(8), o[1], 0, 0, 0);
;   o[0] = __builtin_amdgcn_mfma_f32_32x32x16_bf16(pa1, PKV(2), o[0], 0, 0, 0);
;   o[1] = __builtin_amdgcn_mfma_f32_32x32x16_bf16(pa1, PKV(10), o[1], 0, 0, 0);
;   o[0] = __builtin_amdgcn_mfma_f32_32x32x16_bf16(pa2, PKV(4), o[0], 0, 0, 0);
.Lwd_b:
	s_barrier
	s_waitcnt lgkmcnt(0)
	s_setprio 1
	v_mfma_f32_32x32x16_bf16 v[80:95], v[64:67], v[116:119], v[238:253]
	v_exp_f32_e32 v48, v48
	v_add_f32_e32 v213, v32, v213
	ds_read_b64_tr_b16 v[148:149], v217 offset:0
	v_exp_f32_e32 v49, v49
	v_add_f32_e32 v213, v33, v213
	ds_read_b64_tr_b16 v[150:151], v217 offset:512
	v_mfma_f32_32x32x16_bf16 v[64:79], v[68:71], v[116:119], v[238:253]
	v_exp_f32_e32 v50, v50
	v_add_f32_e32 v213, v34, v213
	ds_read_b64_tr_b16 v[140:141], v217 offset:1024
	v_exp_f32_e32 v51, v51
	v_add_f32_e32 v213, v35, v213
	ds_read_b64_tr_b16 v[142:143], v217 offset:1536
	v_mfma_f32_32x32x16_bf16 v[80:95], v[188:191], v[112:115], v[80:95]
	v_exp_f32_e32 v52, v52
	v_add_f32_e32 v213, v36, v213
	ds_read_b64_tr_b16 v[132:133], v217 offset:2048
	v_exp_f32_e32 v53, v53
	v_add_f32_e32 v213, v37, v213
	ds_read_b64_tr_b16 v[134:135], v217 offset:2560
	v_mfma_f32_32x32x16_bf16 v[64:79], v[184:187], v[112:115], v[64:79]
	v_exp_f32_e32 v54, v54
	v_add_f32_e32 v213, v38, v213
	ds_read_b64_tr_b16 v[124:125], v217 offset:3072
	v_exp_f32_e32 v55, v55
	v_add_f32_e32 v213, v39, v213
	ds_read_b64_tr_b16 v[126:127], v217 offset:3584
	v_mfma_f32_32x32x16_bf16 v[80:95], v[180:183], v[108:111], v[80:95]
	v_exp_f32_e32 v56, v56
	v_add_f32_e32 v213, v40, v213
	ds_read_b64_tr_b16 v[144:145], v217 offset:4096
	v_exp_f32_e32 v57, v57
	v_add_f32_e32 v213, v41, v213
	ds_read_b64_tr_b16 v[146:147], v217 offset:4608
	v_mfma_f32_32x32x16_bf16 v[64:79], v[176:179], v[108:111], v[64:79]
	v_exp_f32_e32 v58, v58
	v_add_f32_e32 v213, v42, v213
	ds_read_b64_tr_b16 v[136:137], v217 offset:5120
	v_exp_f32_e32 v59, v59
	v_add_f32_e32 v213, v43, v213
	ds_read_b64_tr_b16 v[138:139], v217 offset:5632
	v_mfma_f32_32x32x16_bf16 v[80:95], v[172:175], v[104:107], v[80:95]
	v_exp_f32_e32 v60, v60
	v_add_f32_e32 v213, v44, v213
	ds_read_b64_tr_b16 v[128:129], v217 offset:6144
	v_exp_f32_e32 v61, v61
	v_add_f32_e32 v213, v45, v213
	ds_read_b64_tr_b16 v[130:131], v217 offset:6656
	v_mfma_f32_32x32x16_bf16 v[64:79], v[168:171], v[104:107], v[64:79]
	v_exp_f32_e32 v62, v62
	v_add_f32_e32 v213, v46, v213
	ds_read_b64_tr_b16 v[120:121], v217 offset:7168
	v_exp_f32_e32 v63, v63
	v_add_f32_e32 v213, v47, v213
	ds_read_b64_tr_b16 v[122:123], v217 offset:7680
	v_mfma_f32_32x32x16_bf16 v[80:95], v[164:167], v[100:103], v[80:95]
	v_add_f32_e32 v237, v48, v49
	v_add_f32_e32 v237, v50, v237
	v_add_f32_e32 v237, v51, v237
	v_add_f32_e32 v237, v52, v237
	v_add_f32_e32 v237, v53, v237
	v_add_f32_e32 v237, v54, v237
	v_mfma_f32_32x32x16_bf16 v[64:79], v[160:163], v[100:103], v[64:79]
	v_add_f32_e32 v237, v55, v237
	v_add_f32_e32 v237, v56, v237
	v_add_f32_e32 v237, v57, v237
	v_add_f32_e32 v237, v58, v237
	v_add_f32_e32 v237, v59, v237
	v_mfma_f32_32x32x16_bf16 v[80:95], v[156:159], v[96:99], v[80:95]
	v_add_f32_e32 v237, v60, v237
	v_add_f32_e32 v237, v61, v237
	v_add_f32_e32 v237, v62, v237
	v_add_f32_e32 v237, v63, v237
	v_add_f32_e32 v213, v237, v213
	v_cvt_pk_bf16_f32 v32, v32, v33
	v_mfma_f32_32x32x16_bf16 v[64:79], v[152:155], v[96:99], v[64:79]
	v_cvt_pk_bf16_f32 v33, v34, v35
	v_cvt_pk_bf16_f32 v34, v36, v37
	v_cvt_pk_bf16_f32 v35, v38, v39
	v_cvt_pk_bf16_f32 v36, v40, v41
	v_cvt_pk_bf16_f32 v37, v42, v43
	v_cvt_pk_bf16_f32 v38, v44, v45
	s_waitcnt lgkmcnt(0)
	v_mfma_f32_32x32x16_bf16 v[0:15], v[32:35], v[148:151], v[0:15]
	v_cvt_pk_bf16_f32 v39, v46, v47
	v_cvt_pk_bf16_f32 v48, v48, v49
	v_cvt_pk_bf16_f32 v49, v50, v51
	v_cvt_pk_bf16_f32 v50, v52, v53
	v_mfma_f32_32x32x16_bf16 v[16:31], v[32:35], v[144:147], v[16:31]
	v_cvt_pk_bf16_f32 v51, v54, v55
	v_cvt_pk_bf16_f32 v52, v56, v57
	v_cvt_pk_bf16_f32 v53, v58, v59
	v_cvt_pk_bf16_f32 v54, v60, v61
	v_cvt_pk_bf16_f32 v55, v62, v63
	v_mfma_f32_32x32x16_bf16 v[0:15], v[36:39], v[140:143], v[0:15]
	v_exp_f32_e32 v40, v88
	v_exp_f32_e32 v41, v89
	v_exp_f32_e32 v42, v90
	v_mfma_f32_32x32x16_bf16 v[16:31], v[36:39], v[136:139], v[16:31]
	v_exp_f32_e32 v43, v91
	v_exp_f32_e32 v44, v92
	v_exp_f32_e32 v45, v93
	v_mfma_f32_32x32x16_bf16 v[0:15], v[48:51], v[132:135], v[0:15]
	v_exp_f32_e32 v46, v94
	v_exp_f32_e32 v47, v95
	v_exp_f32_e32 v32, v80
	v_mfma_f32_32x32x16_bf16 v[16:31], v[48:51], v[128:131], v[16:31]
	v_exp_f32_e32 v33, v81
	v_exp_f32_e32 v34, v82
	v_exp_f32_e32 v35, v83
	v_mfma_f32_32x32x16_bf16 v[0:15], v[52:55], v[124:127], v[0:15]
	v_exp_f32_e32 v36, v84
	v_exp_f32_e32 v37, v85
	v_mfma_f32_32x32x16_bf16 v[16:31], v[52:55], v[120:123], v[16:31]
	v_exp_f32_e32 v38, v86
	v_exp_f32_e32 v39, v87
	s_setprio 0
	s_add_i32 s6, s6, 2
	s_barrier
	s_addk_i32 s63, 0x4000
	v_lshl_add_u64 v[220:221], v[220:221], 0, s[12:13]
	v_lshl_add_u64 v[222:223], v[222:223], 0, s[10:11]
	v_lshl_add_u64 v[224:225], v[224:225], 0, s[10:11]
	s_and_b64 vcc, exec, s[58:59]
	s_cbranch_vccnz .LBB0_597
	s_mov_b32 s68, s70
	s_mov_b32 s70, s71
	s_branch .LBB0_570

; __device__ __forceinline__ void finishSM2(f32x16& p0, f32x16& p1, float alpha, float& l_reg, bf16x8& pa0, bf16x8& pa1, bf16x8& pa2, bf16x8& pa3) {
; #pragma unroll
;   for (int r = 0; r < 16; ++r) p1[r] = __builtin_amdgcn_exp2f(p1[r]);
;   float ps = 0;
; #pragma unroll
;   for (int r = 0; r < 16; ++r) ps += p0[r];
; #pragma unroll
;   for (int r = 0; r < 16; ++r) ps += p1[r];
;   { auto rr = __builtin_amdgcn_permlane32_swap(__float_as_uint(ps), __float_as_uint(ps), false, false);
;     ps = __uint_as_float(rr[0]) + __uint_as_float(rr[1]); }
;   l_reg = l_reg * alpha + ps;
;     ...
;   PK8(p0, 0, pa0); PK8(p0, 8, pa1); PK8(p1, 0, pa2); PK8(p1, 8, pa3);
;     ...
; }
; __device__ __forceinline__ void kload12(bf16x8* kf, const LAS char* Ks, int r32, int hi) {
;   const LAS char* kb = Ks + hi * 1024 + r32 * 16;
; #pragma unroll
;   for (int d0 = 0; d0 < 6; ++d0) { kf[2 * d0] = *(const LAS bf16x8*)(kb + d0 * 2048); kf[2 * d0 + 1] = *(const LAS bf16x8*)(kb + d0 * 2048 + 512); }
; }
; __device__ __forceinline__ void qkt3(f32x16& p0, f32x16& p1, const bf16x8* kf, const bf16x8* qr) {
;   p0 = f32x16{}; p1 = f32x16{};
; #pragma unroll
;   for (int d0 = 0; d0 < 6; ++d0) {
;     p0 = __builtin_amdgcn_mfma_f32_32x32x16_bf16(kf[2 * d0], qr[d0], p0, 0, 0, 0);
;     p1 = __builtin_amdgcn_mfma_f32_32x32x16_bf16(kf[2 * d0 + 1], qr[d0], p1, 0, 0, 0); }
; }
; __device__ __forceinline__ void vload16(s16x4* vf, int vb) {
;   vf[0] = tr_read<0>(vb); vf[1] = tr_read<512>(vb); vf[2] = tr_read<1024>(vb); vf[3] = tr_read<1536>(vb);
;   vf[4] = tr_read<2048>(vb); vf[5] = tr_read<2560>(vb); vf[6] = tr_read<3072>(vb); vf[7] = tr_read<3584>(vb);
;   vf[8] = tr_read<4096>(vb); vf[9] = tr_read<4608>(vb); vf[10] = tr_read<5120>(vb); vf[11] = tr_read<5632>(vb);
;   vf[12] = tr_read<6144>(vb); vf[13] = tr_read<6656>(vb); vf[14] = tr_read<7168>(vb); vf[15] = tr_read<7680>(vb);
; }
; __device__ __forceinline__ void pv3(f32x16* o, const s16x4* vf, bf16x8 pa0, bf16x8 pa1, bf16x8 pa2, bf16x8 pa3) {
;     ...
;   o[0] = __builtin_amdgcn_mfma_f32_32x32x16_bf16(pa0, PKV(0), o[0], 0, 0, 0);
;   o[1] = __builtin_amdgcn_mfma_f32_32x32x16_bf16(pa0, PKV(8), o[1], 0, 0, 0);
;   o[0] = __builtin_amdgcn_mfma_f32_32x32x16_bf16(pa1, PKV(2), o[0], 0, 0, 0);
;   o[1] = __builtin_amdgcn_mfma_f32_32x32x16_bf16(pa1, PKV(10), o[1], 0, 0, 0);
;   o[0] = __builtin_amdgcn_mfma_f32_32x32x16_bf16(pa2, PKV(4), o[0], 0, 0, 0);
.Ljoin_u:
	ds_read_b128 v[48:51], v231 offset:36864
	ds_read_b128 v[52:55], v231 offset:37376
	ds_read_b128 v[188:191], v231 offset:38912
	ds_read_b128 v[184:187], v231 offset:39424
	ds_read_b128 v[180:183], v231 offset:40960
	ds_read_b128 v[176:179], v231 offset:41472
	ds_read_b128 v[172:175], v231 offset:43008
	ds_read_b128 v[168:171], v231 offset:43520
	ds_read_b128 v[164:167], v231 offset:45056
	ds_read_b128 v[160:163], v231 offset:45568
	ds_read_b128 v[156:159], v231 offset:47104
	ds_read_b128 v[152:155], v231 offset:47616
	s_waitcnt vmcnt(0) lgkmcnt(0)
	s_barrier
	s_waitcnt lgkmcnt(0)
	s_setprio 1
	v_mfma_f32_32x32x16_bf16 v[80:95], v[48:51], v[116:119], v[238:253]
	v_exp_f32_e32 v64, v64
	v_add_f32_e32 v213, v32, v213
	ds_read_b64_tr_b16 v[148:149], v233 offset:0
	v_exp_f32_e32 v65, v65
	v_add_f32_e32 v213, v33, v213
	ds_read_b64_tr_b16 v[150:151], v233 offset:512
	v_mfma_f32_32x32x16_bf16 v[48:63], v[52:55], v[116:119], v[238:253]
	v_exp_f32_e32 v66, v66
	v_add_f32_e32 v213, v34, v213
	ds_read_b64_tr_b16 v[140:141], v233 offset:1024
	v_exp_f32_e32 v67, v67
	v_add_f32_e32 v213, v35, v213
	ds_read_b64_tr_b16 v[142:143], v233 offset:1536
	v_mfma_f32_32x32x16_bf16 v[80:95], v[188:191], v[112:115], v[80:95]
	v_exp_f32_e32 v68, v68
	v_add_f32_e32 v213, v36, v213
	ds_read_b64_tr_b16 v[132:133], v233 offset:2048
	v_exp_f32_e32 v69, v69
	v_add_f32_e32 v213, v37, v213
	ds_read_b64_tr_b16 v[134:135], v233 offset:2560
	v_mfma_f32_32x32x16_bf16 v[48:63], v[184:187], v[112:115], v[48:63]
	v_exp_f32_e32 v70, v70
	v_add_f32_e32 v213, v38, v213
	ds_read_b64_tr_b16 v[124:125], v233 offset:3072
	v_exp_f32_e32 v71, v71
	v_add_f32_e32 v213, v39, v213
	ds_read_b64_tr_b16 v[126:127], v233 offset:3584
	v_mfma_f32_32x32x16_bf16 v[80:95], v[180:183], v[108:111], v[80:95]
	v_exp_f32_e32 v72, v72
	v_add_f32_e32 v213, v40, v213
	ds_read_b64_tr_b16 v[144:145], v233 offset:4096
	v_exp_f32_e32 v73, v73
	v_add_f32_e32 v213, v41, v213
	ds_read_b64_tr_b16 v[146:147], v233 offset:4608
	v_mfma_f32_32x32x16_bf16 v[48:63], v[176:179], v[108:111], v[48:63]
	v_exp_f32_e32 v74, v74
	v_add_f32_e32 v213, v42, v213
	ds_read_b64_tr_b16 v[136:137], v233 offset:5120
	v_exp_f32_e32 v75, v75
	v_add_f32_e32 v213, v43, v213
	ds_read_b64_tr_b16 v[138:139], v233 offset:5632
	v_mfma_f32_32x32x16_bf16 v[80:95], v[172:175], v[104:107], v[80:95]
	v_exp_f32_e32 v76, v76
	v_add_f32_e32 v213, v44, v213
	ds_read_b64_tr_b16 v[128:129], v233 offset:6144
	v_exp_f32_e32 v77, v77
	v_add_f32_e32 v213, v45, v213
	ds_read_b64_tr_b16 v[130:131], v233 offset:6656
	v_mfma_f32_32x32x16_bf16 v[48:63], v[168:171], v[104:107], v[48:63]
	v_exp_f32_e32 v78, v78
	v_add_f32_e32 v213, v46, v213
	ds_read_b64_tr_b16 v[120:121], v233 offset:7168
	v_exp_f32_e32 v79, v79
	v_add_f32_e32 v213, v47, v213
	ds_read_b64_tr_b16 v[122:123], v233 offset:7680
	v_mfma_f32_32x32x16_bf16 v[80:95], v[164:167], v[100:103], v[80:95]
	v_add_f32_e32 v237, v64, v65
	v_add_f32_e32 v237, v66, v237
	v_add_f32_e32 v237, v67, v237
	v_add_f32_e32 v237, v68, v237
	v_add_f32_e32 v237, v69, v237
	v_add_f32_e32 v237, v70, v237
	v_mfma_f32_32x32x16_bf16 v[48:63], v[160:163], v[100:103], v[48:63]
	v_add_f32_e32 v237, v71, v237
	v_add_f32_e32 v237, v72, v237
	v_add_f32_e32 v237, v73, v237
	v_add_f32_e32 v237, v74, v237
	v_add_f32_e32 v237, v75, v237
	v_mfma_f32_32x32x16_bf16 v[80:95], v[156:159], v[96:99], v[80:95]
	v_add_f32_e32 v237, v76, v237
	v_add_f32_e32 v237, v77, v237
	v_add_f32_e32 v237, v78, v237
	v_add_f32_e32 v237, v79, v237
	v_add_f32_e32 v213, v237, v213
	v_cvt_pk_bf16_f32 v32, v32, v33
	v_mfma_f32_32x32x16_bf16 v[48:63], v[152:155], v[96:99], v[48:63]
	v_cvt_pk_bf16_f32 v33, v34, v35
	v_cvt_pk_bf16_f32 v34, v36, v37
	v_cvt_pk_bf16_f32 v35, v38, v39
	v_cvt_pk_bf16_f32 v36, v40, v41
	v_cvt_pk_bf16_f32 v37, v42, v43
	v_cvt_pk_bf16_f32 v38, v44, v45
	s_waitcnt lgkmcnt(0)
	v_mfma_f32_32x32x16_bf16 v[0:15], v[32:35], v[148:151], v[0:15]
	v_cvt_pk_bf16_f32 v39, v46, v47
	v_cvt_pk_bf16_f32 v64, v64, v65
	v_cvt_pk_bf16_f32 v65, v66, v67
	v_cvt_pk_bf16_f32 v66, v68, v69
	v_mfma_f32_32x32x16_bf16 v[16:31], v[32:35], v[144:147], v[16:31]
	v_cvt_pk_bf16_f32 v67, v70, v71
	v_cvt_pk_bf16_f32 v68, v72, v73
	v_cvt_pk_bf16_f32 v69, v74, v75
	v_cvt_pk_bf16_f32 v70, v76, v77
	v_cvt_pk_bf16_f32 v71, v78, v79
	v_mfma_f32_32x32x16_bf16 v[0:15], v[36:39], v[140:143], v[0:15]
	v_exp_f32_e32 v40, v88
	v_exp_f32_e32 v41, v89
	v_exp_f32_e32 v42, v90
	v_mfma_f32_32x32x16_bf16 v[16:31], v[36:39], v[136:139], v[16:31]
	v_exp_f32_e32 v43, v91
	v_exp_f32_e32 v44, v92
	v_exp_f32_e32 v45, v93
	v_mfma_f32_32x32x16_bf16 v[0:15], v[64:67], v[132:135], v[0:15]
	v_exp_f32_e32 v46, v94
	v_exp_f32_e32 v47, v95
	v_exp_f32_e32 v32, v80
	v_mfma_f32_32x32x16_bf16 v[16:31], v[64:67], v[128:131], v[16:31]
	v_exp_f32_e32 v33, v81
	v_exp_f32_e32 v34, v82
	v_exp_f32_e32 v35, v83
	v_mfma_f32_32x32x16_bf16 v[0:15], v[68:71], v[124:127], v[0:15]
	v_exp_f32_e32 v36, v84
	v_exp_f32_e32 v37, v85
	v_mfma_f32_32x32x16_bf16 v[16:31], v[68:71], v[120:123], v[16:31]
	v_exp_f32_e32 v38, v86
	v_exp_f32_e32 v39, v87
	s_setprio 0
	s_barrier
	s_and_b64 vcc, exec, s[4:5]
	s_cbranch_vccnz .LBB0_603
	s_barrier
